# E32 conv tap-weight LDS fill: four serialized load-wait-write round trips batched into one
# speedup vs baseline: 1.0027x; 1.0017x over previous
; #define LAS __attribute__((address_space(3)))
; #define AIN(k) ((const float*)argp(lds, (k)))
; __global__ void __launch_bounds__(NWAVES * 64, 2) fwd_kernel(KArgs a) {
;     ...
;             PHASE_PTRS();
;     ...
;             { const float* dw = AIN(6) + l * 31 * 256; const int tl = wave * 64 + ln;
;               for (int i = tl; i < 31 * 64; i += NWAVES * 64) ((LAS f32x4*)lds)[i] = ((const f32x4*)dw)[i];
;               __syncthreads(); }
.LBB0_322:
	s_or_b64 exec, exec, s[0:1]
	v_readlane_b32 s0, v215, 32
	v_readlane_b32 s1, v215, 33
	s_xor_b64 s[0:1], s[0:1], -1
	v_writelane_b32 v215, s0, 43
	s_waitcnt lgkmcnt(0)
	s_barrier
	v_writelane_b32 v215, s1, 44
	s_nop 0
	v_readlane_b32 s0, v215, 0
	v_readlane_b32 s54, v254, 6
	s_nop 0
	v_mov_b32_e32 v0, s0
	ds_read_b64 v[0:1], v0
	s_mov_b32 s0, s96
	v_mbcnt_lo_u32_b32 v2, -1, 0
	v_mbcnt_hi_u32_b32 v2, -1, v2
	s_waitcnt lgkmcnt(0)
	v_readfirstlane_b32 s42, v0
	v_mov_b32_e32 v0, s0
	v_readfirstlane_b32 s43, v1
	ds_read_b64 v[0:1], v0
	v_readlane_b32 s0, v215, 17
	s_waitcnt lgkmcnt(0)
	s_nop 0
	v_mov_b32_e32 v0, s0
	ds_read_b64 v[0:1], v0
	v_readlane_b32 s0, v254, 45
	s_waitcnt lgkmcnt(0)
	v_readfirstlane_b32 s3, v0
	v_add_u32_e32 v0, s0, v2
	s_movk_i32 s0, 0x7c0
	v_readfirstlane_b32 s2, v1
	v_cmp_gt_i32_e32 vcc, s0, v0
	s_and_saveexec_b64 s[0:1], vcc
	s_cbranch_execz .LBB0_325
	v_readlane_b32 s4, v254, 46
	v_ashrrev_i32_e32 v1, 31, v0
	s_nop 0
	v_add_u32_e32 v3, s4, v2
	v_readlane_b32 s4, v215, 40
	v_readlane_b32 s5, v215, 41
	s_mul_hi_u32 s5, s4, 0x7c00
	s_mulk_i32 s4, 0x7c00
	s_add_u32 s4, s3, s4
	s_addc_u32 s5, s2, s5
	v_readlane_b32 s2, v254, 47
	v_lshl_add_u64 v[0:1], v[0:1], 4, s[4:5]
	s_nop 0
	v_lshl_add_u32 v2, v2, 4, s2
	s_mov_b64 s[2:3], 0
	global_load_dwordx4 v[4:7], v[0:1], off
	v_lshl_add_u64 v[8:9], v[0:1], 0, s[50:51]
	v_lshl_add_u64 v[10:11], v[8:9], 0, s[50:51]
	v_lshl_add_u64 v[20:21], v[10:11], 0, s[50:51]
	global_load_dwordx4 v[12:15], v[8:9], off
	global_load_dwordx4 v[16:19], v[10:11], off
	s_movk_i32 s4, 0xffc0
	v_cmp_gt_i32_e32 vcc, s4, v3
	s_and_saveexec_b64 s[2:3], vcc
	global_load_dwordx4 v[24:27], v[20:21], off
	s_or_b64 exec, exec, s[2:3]
	s_waitcnt vmcnt(0)
	ds_write_b128 v2, v[4:7]
	ds_write_b128 v2, v[12:15] offset:8192
	ds_write_b128 v2, v[16:19] offset:16384
	s_and_b64 exec, exec, vcc
	ds_write_b128 v2, v[24:27] offset:24576
